# GDN chunk loop: next-chunk load pointers and o store pointer advanced by single 64-bit adds with SGPR strides (was add/nop/addc triplets); includes norm partial batching and process address hoist
# speedup vs baseline: 1.0001x; 1.0001x over previous
; #define LAS __attribute__((address_space(3)))
; __device__ __forceinline__ float hload(const f16_t* p) { return (float)(*p); }
; __device__ __forceinline__ int tidx() { int t = threadIdx.x; asm volatile("" : "+v"(t)); return t; }
; template <int MIX, bool SAMPLE>
; __device__ __forceinline__ void rec_load(Raw<MIX>& R, const f16_t* proj, int chunk, int sg, int head, int vcol0) {
;     const int tid = tidx(), s = tid >> 3, cgi = tid & 7;
;     const Slot sl = slot_of<SAMPLE>(chunk, s, sg);
;     const f16_t* rowp = proj + (size_t)sl.row * PN;
;     if constexpr (MIX == 0) {
;         R.hq = *(const u32x4*)(rowp + C_HQ + head * 64 + cgi * 8);
;         R.hf = *(const u32x4*)(rowp + C_HF + head * 64 + cgi * 8);
;         R.hi = *(const u32x2*)(rowp + C_HI + head * 64 + vcol0 + cgi * 4);
;     } else if constexpr (MIX == 1) {
;         R.q = *(const u32x4*)(rowp + C_GQKV + head * 64 + cgi * 8);
;         R.k = *(const u32x4*)(rowp + C_GQKV + 256 + head * 64 + cgi * 8);
;         R.v = *(const u32x2*)(rowp + C_GQKV + 512 + head * 64 + vcol0 + cgi * 4);
;         R.ga = hload(rowp + C_GA + head); R.gb = hload(rowp + C_GB + head);
;     ...
;     if constexpr (MIX == 1) {
;         constexpr int BUF = C::OFF_O + 2048;
;         rec_load<MIX, false>(R, proj, 0, sg, head, vcol0);
;         rec_process<MIX, false>(R, par, l, L, 0, sg, head);
;         __syncthreads();
;         rec_load<MIX, false>(R, proj, 1, sg, head, vcol0);
; #pragma unroll 1
;         for (int c = 0; c < SEQ / 64; ++c) {
;             LAS float* Lc = L + (c & 1) * BUF;
; #pragma unroll 1
;             for (int g = 0; g < (act ? 4 : 0); ++g) { float pp[16];
.LBB0_410:
	s_or_b64 exec, exec, s[4:5]
	v_mov_b32_e32 v0, v202
	s_waitcnt lgkmcnt(0)
	s_barrier
	s_mov_b64 s[98:99], 0x20000
	s_mov_b64 s[100:101], 0x88000
	s_lshl_b32 s2, s30, 6
	v_ashrrev_i32_e32 v1, 3, v0
	v_and_b32_e32 v2, 7, v0
	v_add3_u32 v3, v1, s10, 64
	v_mov_b64_e32 v[0:1], s[54:55]
	s_lshl_b32 s11, s34, 5
	v_mad_i64_i32 v[12:13], s[4:5], v3, s18, v[0:1]
	s_lshl_b32 s78, s2, 1
	s_mov_b32 s57, s79
	v_lshl_add_u64 v[8:9], v[12:13], 0, s[78:79]
	v_lshlrev_b32_e32 v0, 4, v2
	v_mov_b32_e32 v1, v17
	s_lshl_b32 s4, s11, 1
	s_mov_b32 s5, s79
	v_lshl_add_u64 v[12:13], v[12:13], 0, s[56:57]
	v_lshlrev_b32_e32 v16, 3, v2
	s_waitcnt vmcnt(0)
	v_lshl_add_u64 v[4:5], v[8:9], 0, v[0:1]
	v_lshl_add_u64 v[8:9], v[8:9], 0, s[4:5]
	v_add_co_u32_e32 v12, vcc, s20, v12
	v_lshl_add_u64 v[8:9], v[8:9], 0, v[16:17]
	s_nop 0
	v_addc_co_u32_e32 v13, vcc, 0, v13, vcc
	v_add_co_u32_e32 v176, vcc, 0x88000, v4
	s_nop 1
	v_addc_co_u32_e32 v177, vcc, 0, v5, vcc
	v_add_co_u32_e32 v178, vcc, 0x88000, v8
	s_nop 1
	v_addc_co_u32_e32 v179, vcc, 0, v9, vcc
	v_add_co_u32_e32 v180, vcc, 0x88000, v12
	s_nop 1
	v_addc_co_u32_e32 v181, vcc, 0, v13, vcc
	global_load_dwordx4 v[0:3], v[4:5], off offset:2048
	s_nop 0
	global_load_dwordx4 v[4:7], v[4:5], off offset:2560
	v_bfe_u32 v21, v10, 4, 2
	global_load_dwordx2 v[8:9], v[8:9], off offset:3072
	v_ashrrev_i32_e32 v11, 4, v10
	global_load_ushort v23, v[12:13], off
	v_and_b32_e32 v20, 15, v10
	global_load_ushort v24, v[12:13], off offset:8
	v_and_b32_e32 v13, 2, v10
	v_and_b32_e32 v22, -4, v11
	s_add_i32 s2, 0, 0x8000
	v_cmp_gt_i32_e64 s[42:43], 32, v22
	s_mov_b32 s12, 0
	v_cmp_gt_u32_e64 s[44:45], 8, v20
	v_cmp_eq_u32_e64 s[48:49], 0, v13
	s_or_b32 s13, s10, 0x80
	v_lshl_add_u32 v26, v20, 4, 0
	v_and_b32_e32 v12, 4, v10
	v_and_b32_e32 v10, 1, v10
	v_cmp_eq_u32_e64 s[50:51], 0, v10
	v_lshlrev_b32_e32 v10, 2, v11
	v_lshlrev_b32_e32 v11, 2, v21
	v_and_or_b32 v10, v10, -16, v11
	v_add_u32_e32 v25, s2, v10
	v_lshlrev_b32_e32 v11, 7, v20
	s_add_i32 s2, 0, 0xc400
	v_add3_u32 v27, v10, v11, s2
	v_mov_b32_e32 v10, 0
	v_cmp_eq_u32_e64 s[46:47], 0, v12
	v_mov_b32_e32 v11, v10
	v_mov_b32_e32 v12, v10
	v_mov_b32_e32 v13, v10
	v_ashrrev_i32_e32 v187, 3, v202
	v_lshlrev_b32_e32 v186, 2, v202
	v_and_b32_e32 v186, 28, v186
	v_lshlrev_b32_e32 v182, 7, v187
	v_lshl_add_u32 v182, v186, 2, v182
	v_and_b32_e32 v194, 7, v202
	v_lshlrev_b32_e32 v192, 8, v187
	v_lshl_add_u32 v192, v194, 5, v192
	v_lshlrev_b32_e32 v193, 7, v187
	v_lshl_add_u32 v193, v194, 4, v193
	v_lshlrev_b32_e32 v194, 4, v187
	v_add_u32_e32 v184, s10, v187
	v_ashrrev_i32_e32 v185, 31, v184
	v_lshlrev_b64 v[184:185], 11, v[184:185]
	v_lshl_add_u64 v[184:185], s[52:53], 0, v[184:185]
	v_lshl_add_u64 v[184:185], v[184:185], 0, s[78:79]
	v_lshl_add_u64 v[184:185], v[184:185], 0, s[4:5]
	v_lshlrev_b32_e32 v186, 1, v186
	v_mov_b32_e32 v187, 0
	v_lshl_add_u64 v[184:185], v[184:185], 0, v[186:187]
	v_add_co_u32_e32 v184, vcc, 0x3500000, v184
	s_nop 1
	v_addc_co_u32_e32 v185, vcc, 0, v185, vcc
	s_bitcmp1_b32 s12, 0
	s_cselect_b32 s22, 0x3900, 0
	s_and_saveexec_b64 s[6:7], s[42:43]
	s_cbranch_execz .LBB0_413

; #define LAS __attribute__((address_space(3)))
; __device__ __forceinline__ int tidx() { int t = threadIdx.x; asm volatile("" : "+v"(t)); return t; }
;     typedef RecCfg<MIX> C;
;     const int tid = tidx(), s = tid >> 3, c4 = (tid & 7) * 4;
;     const Slot sl = slot_of<SAMPLE>(chunk, s, sg);
;     f32x4 o = *(const LAS f32x4*)(L + C::OFF_O + s * 32 + c4);
;     if constexpr (MIX == 3) o = o + *(const LAS f32x4*)(L + C::OFF_XSD + s * 32 + c4);
;     u32x2 w; w.x = pkh(o[0], o[1]); w.y = pkh(o[2], o[3]);
;     if (c4 < nv) *(u32x2*)(raw + (size_t)sl.row * DM + mixer * 256 + head * 64 + vcol0 + c4) = w;
;     ...
;             if (c + 1 < SEQ / 64) { rec_process<MIX, false>(R, par, l, L + ((c + 1) & 1) * BUF, c + 1, sg, head);
;                 if (c + 2 < SEQ / 64) rec_load<MIX, false>(R, proj, c + 2, sg, head, vcol0);
;                 else if (DO_SAMPLE) rec_load<MIX, true>(R, proj, 0, sg, head, vcol0); }
;             __syncthreads();
;             rec_store_o<MIX, false>(Lc, raw, c, sg, MIX, head, vcol0, nv);
.LBB0_418:
	s_or_b64 exec, exec, s[6:7]
	s_cmp_gt_u32 s12, 29
	s_cbranch_scc1 .LBB0_420
	global_load_dwordx2 v[8:9], v[178:179], off offset:3072
	global_load_ushort v23, v[180:181], off
	global_load_ushort v24, v[180:181], off offset:8
	global_load_dwordx4 v[0:3], v[176:177], off offset:2048
	global_load_dwordx4 v[4:7], v[176:177], off offset:2560
	v_lshl_add_u64 v[176:177], v[176:177], 0, s[100:101]
	s_mov_b32 s5, s79
	v_lshl_add_u64 v[178:179], v[178:179], 0, s[100:101]
	v_lshl_add_u64 v[180:181], v[180:181], 0, s[100:101]
.LBB0_420:
	s_waitcnt lgkmcnt(0)
	s_barrier
	s_lshl_b32 s3, s22, 2
	s_mov_b32 s5, s79
	v_add_u32_e32 v14, s3, v182
	ds_read_b128 v[188:191], v14 offset:50176
	s_cmp_eq_u32 s2, 32
	s_cbranch_scc1 .Lgdn_last_o
	s_mov_b32 s12, s2
	s_bitcmp1_b32 s12, 0
	s_cselect_b32 s22, 0x3900, 0
	s_and_saveexec_b64 s[6:7], s[42:43]
	s_cbranch_execz .Lgdn_o_noloop
	s_lshl_b32 s5, s22, 2
	s_mov_b32 s8, 4
	s_add_i32 s2, s17, s5
	v_add_u32_e32 v172, s5, v26
	v_add_u32_e32 v173, s5, v25
	v_mov_b32_e32 v174, s2
	v_bfrev_b32_e32 v175, v20
	s_movk_i32 s3, 0x4400
	v_lshrrev_b32_e32 v175, 28, v175
	v_lshlrev_b32_e32 v175, 7, v175
	v_add3_u32 v175, v175, v173, s3
	ds_read_b128 v[28:31], v172 offset:0
	ds_read_b128 v[32:35], v172 offset:16384
	ds_read_b128 v[36:39], v172 offset:256
	ds_read_b128 v[40:43], v172 offset:16640
	ds_read_b128 v[44:47], v172 offset:512
	ds_read_b128 v[48:51], v172 offset:16896
	ds_read_b128 v[52:55], v172 offset:768
	ds_read_b128 v[56:59], v172 offset:17152
	ds_read2_b32 v[60:61], v173 offset1:32
	ds_read2_b32 v[62:63], v173 offset0:64 offset1:96
	ds_read2_b64 v[64:67], v174 offset0:0 offset1:2
	ds_read2_b64 v[68:71], v174 offset0:4 offset1:6
	s_waitcnt lgkmcnt(12)
	v_cvt_pk_f16_f32 v188, v188, v189
	v_cvt_pk_f16_f32 v189, v190, v191
	global_store_dwordx2 v[184:185], v[188:189], off offset:512
	v_lshl_add_u64 v[184:185], v[184:185], 0, s[98:99]
	s_branch .Lgdn_pre_done
.Lgdn_o_noloop:
	s_or_b64 exec, exec, s[6:7]
	s_waitcnt lgkmcnt(0)
	v_cvt_pk_f16_f32 v188, v188, v189
	v_cvt_pk_f16_f32 v189, v190, v191
	global_store_dwordx2 v[184:185], v[188:189], off offset:512
	v_lshl_add_u64 v[184:185], v[184:185], 0, s[98:99]
	s_branch .LBB0_413
.Lgdn_last_o:
	s_waitcnt lgkmcnt(0)
	v_cvt_pk_f16_f32 v188, v188, v189
	v_cvt_pk_f16_f32 v189, v190, v191
	global_store_dwordx2 v[184:185], v[188:189], off offset:512
	v_lshl_add_u64 v[184:185], v[184:185], 0, s[98:99]
